# W_in GEMM epilogue: the 8 serial RS (row sum-of-squares) loads issued together at the first site, one vmcnt wait
# speedup vs baseline: 1.0090x; 1.0090x over previous
; __device__ __forceinline__ void epilogue(const Job& J, const f32x4 (&acc)[2][2][4][2], const pg8::Unit& u, int wr, int wc, int fr, int fq) {
;     ...
;         const int sp = u.pn / J.tps, cn = u.pn - sp * J.tps;
;         f16* base = J.o16 + (size_t)sp * J.split_stride;
;         const int ld = (J.z24 && u.pn == 24) ? 256 : J.ldc;
;         const int col = cn * 256 + J.col_off + ct;
;         float rs[2][4];
; #pragma unroll
;         for (int ai = 0; ai < 2; ++ai)
; #pragma unroll
;             for (int m = 0; m < 4; ++m) rs[ai][m] = J.f0 ? J.f0[row0 + ai * 128 + m * 16] : 1.0f;
; #pragma unroll
;         for (int ai = 0; ai < 2; ++ai)
; #pragma unroll
;             for (int m = 0; m < 4; ++m) { const int row = row0 + ai * 128 + m * 16; f16* rowp = base + (size_t)row * ld + col;
;                 const float r = J.f0 ? __builtin_amdgcn_rsqf(rs[ai][m] * (1.0f / D) + 1e-6f) : 1.0f;
.LBB0_205:
	s_andn2_b64 vcc, exec, s[10:11]
	s_cbranch_vccnz .LBB0_174
	s_cmp_eq_u32 s21, 1
	s_mov_b64 s[10:11], -1
	s_cbranch_scc1 .LBB0_236
	v_cndmask_b32_e64 v136, 0, 1, s[94:95]
	v_mov_b32_e32 v148, 0x3a00431c
	v_cmp_ne_u32_e64 s[10:11], 1, v136
	s_andn2_b64 vcc, exec, s[94:95]
	v_mov_b32_e32 v138, 0x3a00431c
	s_cbranch_vccnz .LBB0_238
	v_ashrrev_i32_e32 v205, 31, v204
	s_waitcnt lgkmcnt(0)
	v_lshl_add_u64 v[136:137], v[204:205], 2, s[56:57]
	global_load_dword v160, v[136:137], off
	global_load_dword v161, v[136:137], off offset:64
	global_load_dword v162, v[136:137], off offset:128
	global_load_dword v163, v[136:137], off offset:192
	global_load_dword v164, v[136:137], off offset:512
	global_load_dword v165, v[136:137], off offset:576
	global_load_dword v166, v[136:137], off offset:640
	global_load_dword v167, v[136:137], off offset:704
	s_waitcnt vmcnt(0)
	v_fmamk_f32 v138, v160, 0x3a000000, v232
	s_and_b64 vcc, exec, s[10:11]
	s_cbranch_vccz .LBB0_239

; __device__ __forceinline__ void epilogue(const Job& J, const f32x4 (&acc)[2][2][4][2], const pg8::Unit& u, int wr, int wc, int fr, int fq) {
;     ...
;             for (int m = 0; m < 4; ++m) rs[ai][m] = J.f0 ? J.f0[row0 + ai * 128 + m * 16] : 1.0f;
; #pragma unroll
;         for (int ai = 0; ai < 2; ++ai)
; #pragma unroll
;             for (int m = 0; m < 4; ++m) { const int row = row0 + ai * 128 + m * 16; f16* rowp = base + (size_t)row * ld + col;
;                 const float r = J.f0 ? __builtin_amdgcn_rsqf(rs[ai][m] * (1.0f / D) + 1e-6f) : 1.0f;
.LBB0_210:
	v_ashrrev_i32_e32 v205, 31, v204
	s_waitcnt lgkmcnt(0)
	v_lshl_add_u64 v[136:137], v[204:205], 2, s[56:57]
	v_fmamk_f32 v147, v162, 0x3a000000, v232
	s_and_b64 vcc, exec, s[10:11]
	s_cbranch_vccz .LBB0_241

; __device__ __forceinline__ void epilogue(const Job& J, const f32x4 (&acc)[2][2][4][2], const pg8::Unit& u, int wr, int wc, int fr, int fq) {
;     ...
;             for (int m = 0; m < 4; ++m) rs[ai][m] = J.f0 ? J.f0[row0 + ai * 128 + m * 16] : 1.0f;
; #pragma unroll
;         for (int ai = 0; ai < 2; ++ai)
; #pragma unroll
;             for (int m = 0; m < 4; ++m) { const int row = row0 + ai * 128 + m * 16; f16* rowp = base + (size_t)row * ld + col;
;                 const float r = J.f0 ? __builtin_amdgcn_rsqf(rs[ai][m] * (1.0f / D) + 1e-6f) : 1.0f;
.LBB0_212:
	v_ashrrev_i32_e32 v205, 31, v204
	s_waitcnt lgkmcnt(0)
	v_lshl_add_u64 v[136:137], v[204:205], 2, s[56:57]
	v_fmamk_f32 v145, v164, 0x3a000000, v232
	s_mov_b64 s[24:25], -1
	s_and_b64 vcc, exec, s[94:95]
	s_cbranch_vccnz .LBB0_243

; __device__ __forceinline__ void epilogue(const Job& J, const f32x4 (&acc)[2][2][4][2], const pg8::Unit& u, int wr, int wc, int fr, int fq) {
;     ...
;             for (int m = 0; m < 4; ++m) rs[ai][m] = J.f0 ? J.f0[row0 + ai * 128 + m * 16] : 1.0f;
; #pragma unroll
;         for (int ai = 0; ai < 2; ++ai)
; #pragma unroll
;             for (int m = 0; m < 4; ++m) { const int row = row0 + ai * 128 + m * 16; f16* rowp = base + (size_t)row * ld + col;
;                 const float r = J.f0 ? __builtin_amdgcn_rsqf(rs[ai][m] * (1.0f / D) + 1e-6f) : 1.0f;
.LBB0_215:
	v_mov_b32_e32 v142, 0x3a00431c
	s_and_b64 vcc, exec, s[10:11]
	s_waitcnt lgkmcnt(0)
	v_lshl_add_u64 v[136:137], v[204:205], 2, s[56:57]
	v_mov_b32_e32 v143, 0x3a00431c
	s_cbranch_vccnz .LBB0_217
	v_fmamk_f32 v143, v166, 0x3a000000, v232
.LBB0_217:
	s_and_b64 vcc, exec, s[10:11]
	s_cbranch_vccnz .LBB0_219
	v_fmamk_f32 v142, v167, 0x3a000000, v232

; __device__ __forceinline__ void epilogue(const Job& J, const f32x4 (&acc)[2][2][4][2], const pg8::Unit& u, int wr, int wc, int fr, int fq) {
;     ...
;             for (int m = 0; m < 4; ++m) rs[ai][m] = J.f0 ? J.f0[row0 + ai * 128 + m * 16] : 1.0f;
; #pragma unroll
;         for (int ai = 0; ai < 2; ++ai)
; #pragma unroll
;             for (int m = 0; m < 4; ++m) { const int row = row0 + ai * 128 + m * 16; f16* rowp = base + (size_t)row * ld + col;
;                 const float r = J.f0 ? __builtin_amdgcn_rsqf(rs[ai][m] * (1.0f / D) + 1e-6f) : 1.0f;
.LBB0_239:
	v_ashrrev_i32_e32 v205, 31, v204
	s_waitcnt lgkmcnt(0)
	v_lshl_add_u64 v[136:137], v[204:205], 2, s[56:57]
	v_fmamk_f32 v148, v161, 0x3a000000, v232
	v_mov_b32_e32 v146, 0x3a00431c
	s_and_b64 vcc, exec, s[10:11]
	v_mov_b32_e32 v147, 0x3a00431c
	s_cbranch_vccz .LBB0_210

; __device__ __forceinline__ void epilogue(const Job& J, const f32x4 (&acc)[2][2][4][2], const pg8::Unit& u, int wr, int wc, int fr, int fq) {
;     ...
;             for (int m = 0; m < 4; ++m) rs[ai][m] = J.f0 ? J.f0[row0 + ai * 128 + m * 16] : 1.0f;
; #pragma unroll
;         for (int ai = 0; ai < 2; ++ai)
; #pragma unroll
;             for (int m = 0; m < 4; ++m) { const int row = row0 + ai * 128 + m * 16; f16* rowp = base + (size_t)row * ld + col;
;                 const float r = J.f0 ? __builtin_amdgcn_rsqf(rs[ai][m] * (1.0f / D) + 1e-6f) : 1.0f;
.LBB0_241:
	v_ashrrev_i32_e32 v205, 31, v204
	s_waitcnt lgkmcnt(0)
	v_lshl_add_u64 v[136:137], v[204:205], 2, s[56:57]
	v_fmamk_f32 v146, v163, 0x3a000000, v232
	s_and_b64 vcc, exec, s[10:11]
	v_mov_b32_e32 v145, 0x3a00431c
	s_cbranch_vccz .LBB0_212

; __device__ __forceinline__ void epilogue(const Job& J, const f32x4 (&acc)[2][2][4][2], const pg8::Unit& u, int wr, int wc, int fr, int fq) {
;     ...
;             for (int m = 0; m < 4; ++m) rs[ai][m] = J.f0 ? J.f0[row0 + ai * 128 + m * 16] : 1.0f;
; #pragma unroll
;         for (int ai = 0; ai < 2; ++ai)
; #pragma unroll
;             for (int m = 0; m < 4; ++m) { const int row = row0 + ai * 128 + m * 16; f16* rowp = base + (size_t)row * ld + col;
;                 const float r = J.f0 ? __builtin_amdgcn_rsqf(rs[ai][m] * (1.0f / D) + 1e-6f) : 1.0f;
.LBB0_243:
	v_ashrrev_i32_e32 v205, 31, v204
	s_waitcnt lgkmcnt(0)
	v_lshl_add_u64 v[136:137], v[204:205], 2, s[56:57]
	v_fmamk_f32 v144, v165, 0x3a000000, v232
	s_cbranch_execz .LBB0_214
	s_branch .LBB0_215
